# phase-3 GEMM jobs: Q and KV jobs start their unit order 160 workgroups later so the three jobs' tail units land on different workgroups
# baseline (speedup 1.0000x reference)
; DEV int vbsel() { return __builtin_amdgcn_readfirstlane((int)(threadIdx.x >> 8)); }
; DEV void ph_prep_early(const P& p, char* smem) {
;   const int skip = gridDim.x > 64 ? 32 : 0;
;   if ((int)blockIdx.x < skip) return;
;   const int vb0 = ((int)blockIdx.x - skip) * 2 + vbsel(), vg = ((int)gridDim.x - skip) * 2;
.LBB0_34:
	s_or_b64 exec, exec, s[2:3]
	s_cmp_gt_u32 s54, 64
	s_cselect_b32 s3, 32, 0
	s_cmp_ge_i32 s73, s3
	s_cselect_b64 s[4:5], -1, 0
	v_writelane_b32 v253, s4, 3
	s_lshl_b32 s91, s54, 1
	s_mul_i32 s2, s55, s54
	v_writelane_b32 v253, s5, 4
	s_sub_i32 s4, s54, s3
	s_lshl_b32 s79, s4, 1
	s_sub_i32 s4, s73, s3
	s_lshl_b32 s4, s4, 1
	s_cmpk_lt_i32 s73, 0x400
	v_writelane_b32 v253, s4, 5
	s_cselect_b64 s[4:5], -1, 0
	v_writelane_b32 v253, s4, 6
	s_cmpk_ge_i32 s54, 0x80
	s_cselect_b32 s4, 64, 0
	s_sub_i32 s4, s73, s4
	s_cmp_lt_u32 s4, 64
	s_barrier
; __device__ __forceinline__ unsigned xb_ld(unsigned* p)              { return __hip_atomic_load(p, __ATOMIC_RELAXED, __HIP_MEMORY_SCOPE_AGENT); }
; __device__ __forceinline__ unsigned xb_add(unsigned* p, unsigned v) { return __hip_atomic_fetch_add(p, v, __ATOMIC_RELAXED, __HIP_MEMORY_SCOPE_AGENT); }
; #define XB_SPIN(cond, bar) do { unsigned _sp = 0; while (cond) { __builtin_amdgcn_s_sleep(1); \
;     if ((++_sp & 255u) == 0u) { if (xb_ld(&(bar)[XB_TMO])) break; if (_sp > XB_SPIN_CAP) { atomicAdd(&(bar)[XB_TMO], 1u); break; } } } } while (0)
; __device__ __forceinline__ void xcd_barrier_complete(unsigned* bar, unsigned x, unsigned& nloc, unsigned& nx) {
;     const unsigned G = gridDim.x * gridDim.y * gridDim.z;
;     unsigned sum, cnt, mine, sp = 0u;
;     for (;;) {
;         sum = 0u; cnt = 0u; mine = 0u;
; #pragma unroll
;         for (unsigned j = 0; j < 16; ++j) { const unsigned c = xb_ld(&bar[XB_XCNT(j)]); sum += c; cnt += (c > 0u) ? 1u : 0u; mine = (j == x) ? c : mine; }
;         if (sum == G) break;
;         __builtin_amdgcn_s_sleep(1);
;         if ((++sp & 255u) == 0u) { if (xb_ld(&bar[XB_TMO])) break; if (sp > XB_SPIN_CAP) { atomicAdd(&bar[XB_TMO], 1u); break; } }
;     }
;     nloc = mine > 0u ? mine : 1u; nx = cnt > 0u ? cnt : 1u;
; }
; __device__ __forceinline__ void xcd_barrier(const XcdBarrier& b) {
;     asm volatile("s_waitcnt vmcnt(0)" ::: "memory");
;     __syncthreads();
;     if (threadIdx.x == 0) {
;         unsigned* bar = b.bar;
;         __builtin_amdgcn_s_waitcnt(0);
;         unsigned nloc = b.st[0], nx = b.st[1];
;         if (nloc == 0u) { xcd_barrier_complete(bar, b.x, nloc, nx); b.st[0] = nloc; b.st[1] = nx; }
;         const unsigned old = xb_add(&bar[XB_XSUB(b.x)], 1u);
;         const unsigned gen = old / nloc;
;         if (old + 1u == (gen + 1u) * nloc) {
;             __builtin_amdgcn_fence(__ATOMIC_RELEASE, "agent");
;             asm volatile("s_waitcnt vmcnt(0)" ::: "memory");
;             const unsigned og = xb_add(&bar[XB_TOP], 1u);
;             const unsigned tg = og / nx;
;             if (og + 1u == (tg + 1u) * nx) xb_add(&bar[XB_TOPGEN], 1u);
;             else XB_SPIN(xb_ld(&bar[XB_TOPGEN]) == tg, bar);
;             __builtin_amdgcn_fence(__ATOMIC_ACQUIRE, "agent");
;             xb_add(&bar[XB_XGEN(b.x)], 1u);
	v_writelane_b32 v253, s5, 7
	s_cselect_b64 s[4:5], -1, 0
	v_writelane_b32 v253, s4, 8
	s_ashr_i32 s55, s73, 31
	s_nop 0
	v_writelane_b32 v253, s5, 9
	s_lshr_b32 s4, s55, 29
	s_add_i32 s4, s73, s4
	s_ashr_i32 s5, s4, 3
	s_and_b32 s4, s4, -8
	v_writelane_b32 v253, s5, 10
	s_sub_i32 s4, s73, s4
	v_writelane_b32 v253, s4, 11
	s_load_dword s4, s[88:89], 0x100
	s_ashr_i32 s51, s54, 31
	s_add_u32 s18, s0, 0x1e4cd200
	s_addc_u32 s19, s1, 0
	s_mov_b32 s28, 0x6dc9c883
	s_waitcnt lgkmcnt(0)
	s_mul_i32 s2, s2, s4
	s_add_u32 s4, s0, 0x1e4cd400
	v_writelane_b32 v253, s2, 12
	s_addc_u32 s5, s1, 0
	v_writelane_b32 v253, s4, 13
	s_mov_b32 s30, 0x54442d18
	v_mbcnt_lo_u32_b32 v0, -1, 0
	v_writelane_b32 v253, s5, 14
	s_add_u32 s4, s0, 0x1e4cd500
	s_addc_u32 s5, s1, 0
	v_writelane_b32 v253, s4, 15
	v_mov_b32_e32 v41, 0
	s_mov_b32 s29, 0x3fc45f30
	v_writelane_b32 v253, s5, 16
	s_add_u32 s4, s0, 0x1e4cd600
	s_addc_u32 s5, s1, 0
	v_writelane_b32 v253, s4, 17
	s_mov_b32 s31, 0xc01921fb
	v_mov_b32_e32 v200, 1
	v_writelane_b32 v253, s5, 18
	s_add_u32 s4, s0, 0x1e4cd700
	s_addc_u32 s5, s1, 0
	v_writelane_b32 v253, s4, 19
	v_mov_b32_e32 v236, 0x7f800000
	v_mbcnt_hi_u32_b32 v237, -1, v0
	v_writelane_b32 v253, s5, 20
	s_add_u32 s4, s0, 0x1e4cd800
	s_addc_u32 s5, s1, 0
	v_writelane_b32 v253, s4, 21
	v_mov_b32_e32 v240, 0x358637bd
	v_mov_b32_e32 v239, 0xcf
	v_writelane_b32 v253, s5, 22
	s_add_u32 s4, s0, 0x1e4cd900
	s_addc_u32 s5, s1, 0
	v_writelane_b32 v253, s4, 23
	v_mov_b32_e32 v248, 0xfcf
	v_mov_b32_e32 v249, 0xdf
	v_writelane_b32 v253, s5, 24
	s_add_u32 s4, s0, 0x1e4cda00
	s_addc_u32 s5, s1, 0
	v_writelane_b32 v253, s4, 25
	v_mov_b32_e32 v243, 0xfdf
	v_mov_b32_e32 v244, 0xef
	v_writelane_b32 v253, s5, 26
	s_add_u32 s4, s0, 0x1e4cdb00
	s_addc_u32 s5, s1, 0
	v_writelane_b32 v253, s4, 27
	v_mov_b32_e32 v245, 0xfef
	v_mov_b32_e32 v235, 0xff
	v_writelane_b32 v253, s5, 28
	s_add_u32 s4, s0, 0x1e4cdc00
	s_addc_u32 s5, s1, 0
	v_writelane_b32 v253, s4, 29
	v_mov_b32_e32 v246, 0xfff
	s_mov_b32 s34, 0x3fb8aa3b
	v_writelane_b32 v253, s5, 30
	s_add_u32 s4, s0, 0x1e4cdd00
	s_addc_u32 s5, s1, 0
	v_writelane_b32 v253, s4, 31
	s_mov_b32 s35, 0xc2ce8ed0
	s_mov_b32 s36, 0x42b17218
	v_writelane_b32 v253, s5, 32
	s_add_u32 s4, s0, 0x1e4cde00
	s_addc_u32 s5, s1, 0
	v_writelane_b32 v253, s4, 33
	s_mov_b32 s52, 0x800000
	s_movk_i32 s53, 0x1600
	v_writelane_b32 v253, s5, 34
	s_add_u32 s4, s0, 0x1e4cdf00
	s_addc_u32 s5, s1, 0
	v_writelane_b32 v253, s4, 35
	s_mov_b32 s85, 0
	s_mov_b64 s[92:93], -1
	v_writelane_b32 v253, s5, 36
	s_add_u32 s4, s0, 0x1e4ce000
	s_addc_u32 s5, s1, 0
	v_writelane_b32 v253, s4, 37
	s_mov_b32 s60, 0x3a800000
	s_mov_b64 s[96:97], 0x80
	v_writelane_b32 v253, s5, 38
	s_add_u32 s4, s0, 0x1e4ce100
	s_addc_u32 s5, s1, 0
	v_writelane_b32 v253, s4, 39
	s_nop 1
	v_writelane_b32 v253, s5, 40
	s_add_u32 s4, s0, 0x1e4ce200
	s_addc_u32 s5, s1, 0
	v_writelane_b32 v253, s4, 41
	s_nop 1
	v_writelane_b32 v253, s5, 42
	s_add_u32 s4, s0, 0x1e4ce300
	s_addc_u32 s5, s1, 0
	v_writelane_b32 v253, s4, 43
	s_cmp_eq_u32 s20, 15
	s_nop 0
	v_writelane_b32 v253, s5, 44
	s_cselect_b64 s[4:5], -1, 0
	v_writelane_b32 v253, s4, 45
	s_cmp_eq_u32 s20, 14
	s_nop 0
	v_writelane_b32 v253, s5, 46
	s_cselect_b64 s[4:5], -1, 0
	v_writelane_b32 v253, s4, 47
	s_cmp_eq_u32 s20, 13
	s_nop 0
	v_writelane_b32 v253, s5, 48
	s_cselect_b64 s[4:5], -1, 0
	v_writelane_b32 v253, s4, 49
	s_cmp_eq_u32 s20, 12
	s_nop 0
	v_writelane_b32 v253, s5, 50
	s_cselect_b64 s[4:5], -1, 0
	v_writelane_b32 v253, s4, 51
	s_cmp_eq_u32 s20, 11
	s_nop 0
	v_writelane_b32 v253, s5, 52
	s_cselect_b64 s[4:5], -1, 0
	v_writelane_b32 v253, s4, 53
	s_cmp_eq_u32 s20, 10
	s_nop 0
	v_writelane_b32 v253, s5, 54
	s_cselect_b64 s[4:5], -1, 0
	v_writelane_b32 v253, s4, 55
	s_cmp_eq_u32 s20, 9
	s_nop 0
	v_writelane_b32 v253, s5, 56
	s_cselect_b64 s[4:5], -1, 0
	v_writelane_b32 v253, s4, 57
	s_cmp_eq_u32 s20, 8
	s_nop 0
	v_writelane_b32 v253, s5, 58
	s_cselect_b64 s[4:5], -1, 0
	v_writelane_b32 v253, s4, 59
	s_cmp_eq_u32 s20, 7
	s_nop 0
	v_writelane_b32 v253, s5, 60
	s_cselect_b64 s[4:5], -1, 0
	v_writelane_b32 v253, s4, 61
	s_cmp_eq_u32 s20, 6
	s_nop 0
	v_writelane_b32 v253, s5, 62
	s_cselect_b64 s[4:5], -1, 0
	v_writelane_b32 v253, s4, 63
	s_cmp_eq_u32 s20, 5
	s_nop 0
	v_writelane_b32 v254, s5, 0
	s_cselect_b64 s[4:5], -1, 0
	v_writelane_b32 v254, s4, 1
	s_cmp_eq_u32 s20, 4
	s_nop 0
	v_writelane_b32 v254, s5, 2
	s_cselect_b64 s[4:5], -1, 0
	v_writelane_b32 v254, s4, 3
	s_cmp_eq_u32 s20, 3
	s_nop 0
	v_writelane_b32 v254, s5, 4
	s_cselect_b64 s[4:5], -1, 0
	v_writelane_b32 v254, s4, 5
	s_cmp_eq_u32 s20, 2
	s_nop 0
	v_writelane_b32 v254, s5, 6
	s_cselect_b64 s[4:5], -1, 0
	v_writelane_b32 v254, s4, 7
	s_cmp_eq_u32 s20, 1
	s_nop 0
	v_writelane_b32 v254, s5, 8
	s_cselect_b64 s[4:5], -1, 0
	v_writelane_b32 v254, s4, 9
	s_cmp_eq_u32 s20, 0
	s_nop 0
	v_writelane_b32 v254, s5, 10
	s_cselect_b64 s[4:5], -1, 0
	s_lshl_b32 s2, s20, 8
	v_writelane_b32 v254, s4, 11
	s_add_u32 s2, s8, s2
	s_movk_i32 s20, 0x400
	v_writelane_b32 v254, s5, 12
	s_addc_u32 s4, s9, 0
	s_add_u32 s6, s2, 0x1400
	s_addc_u32 s7, s4, 0
	v_writelane_b32 v254, s6, 13
	s_nop 1
	v_writelane_b32 v254, s7, 14
	s_add_u32 s6, s2, 0x2400
	s_addc_u32 s7, s4, 0
	v_writelane_b32 v254, s6, 15
	s_add_u32 s4, s0, 0x1e4d0400
	s_addc_u32 s5, s1, 0
	v_writelane_b32 v254, s7, 16
	v_writelane_b32 v254, s4, 17
	s_add_u32 s0, s0, 0x1e4d0500
	s_addc_u32 s1, s1, 0
	v_writelane_b32 v254, s5, 18
	v_writelane_b32 v254, s0, 19
	s_lshl_b32 s33, s54, 9
	s_mov_b32 s4, 0x3f803f80
	v_writelane_b32 v254, s1, 20
	s_lshl_b32 s0, s3, 9
	s_sub_i32 s0, s33, s0
	v_writelane_b32 v254, s0, 21
	s_lshl_b32 s0, s73, 6
	s_or_b32 s0, s0, 8
	v_writelane_b32 v254, s0, 22
	s_lshl_b32 s0, s73, 4
	v_writelane_b32 v254, s0, 23
	s_lshl_b32 s0, s54, 4
	v_writelane_b32 v254, s0, 24
	s_lshl_b32 s0, s54, 6
	v_writelane_b32 v254, s0, 25
	s_lshl_b32 s0, s73, 5
	v_writelane_b32 v254, s0, 26
	s_lshl_b32 s0, s54, 5
	v_writelane_b32 v254, s0, 27
	s_lshl_b32 s0, s73, 9
	v_writelane_b32 v254, s0, 28
	v_writelane_b32 v254, s4, 29
	s_mov_b32 s2, s54
	s_mov_b32 s0, 0
	v_writelane_b32 v254, s5, 30
	v_writelane_b32 v254, s6, 31
	v_writelane_b32 v254, s7, 32
	v_writelane_b32 v254, s73, 33
	s_mov_b32 s32, s73
	v_writelane_b32 v254, s2, 34
	s_nop 1
	v_writelane_b32 v254, s3, 35
	v_writelane_b32 v254, s79, 36
	v_writelane_b32 v254, s55, 37
	v_writelane_b32 v254, s51, 38
	v_writelane_b32 v254, s33, 39
	v_writelane_b32 v254, s88, 40
	s_nop 1
	v_writelane_b32 v254, s89, 41
	v_writelane_b32 v254, s91, 42
	v_writelane_b32 v254, s18, 43
	s_nop 1
	v_writelane_b32 v254, s19, 44
	s_branch .LBB0_36

; DEV void run_job(char* smem_base, const pg8::Job& j) {
;     ...
;   pg8::StaticOrder S; S.init(j.M, j.N, (int)gridDim.x, (int)blockIdx.x);
; __global__ void __launch_bounds__(512) mega(P p_unused) {
;     ...
;         const int nj = n_jobs(ph);
;         if (nj == 0 || ph == 2 || ph == 3) run_phase(kp, ph, l, smem);
;         for (int j = 0; j < nj; ++j) { const pg8::Job jb = get_job(kp, ph, l, j); run_job(smem, jb); }
.LBB0_480:
	s_lshr_b32 s73, s32, 3
	v_writelane_b32 v253, s73, 10
	s_and_b32 s73, s32, 7
	v_writelane_b32 v253, s73, 11
	s_mov_b32 s73, s32
	v_writelane_b32 v254, s73, 33
	s_add_i32 s24, s24, 1
	s_cmp_eq_u32 s24, s65
	s_cbranch_scc1 .LBB0_1101
.LBB0_481:
	s_mov_b32 s73, s32
	v_readlane_b32 s0, v255, 5
	s_cmp_eq_u32 s0, 3
	s_cbranch_scc0 .Ljr_done
	s_cmp_lt_u32 s24, 2
	s_cbranch_scc0 .Ljr_done
	s_cmp_eq_u32 s54, 0x100
	s_cbranch_scc0 .Ljr_done
	s_add_i32 s73, s32, 0x60
	s_and_b32 s73, s73, 0xff
	s_lshr_b32 s0, s73, 3
	v_writelane_b32 v253, s0, 10
	s_and_b32 s0, s73, 7
	v_writelane_b32 v253, s0, 11
	v_writelane_b32 v254, s73, 33
